# GLA prep gate block hand-written: fmac chain with rolling LDS read ring, 8-wide log-sigmoid stages
# speedup vs baseline: 1.0232x; 1.0232x over previous
; DI float bflo(unsigned w) { return __uint_as_float(w << 16); }
; DI float bfhi(unsigned w) { return __uint_as_float(w & 0xffff0000u); }
; DI void gla_prep_item(const Args& A, int l, unsigned char* ldsb, int item, int tid, bool stage) {
;     ...
;     {
;         float cf[32];
; #pragma unroll
;         for (int j = 0; j < 4; ++j) { const u32x4 v = j == 0 ? cq0 : (j == 1 ? cq1 : (j == 2 ? cq2 : cq3)); cf[8 * j + 0] = bflo(v.x); cf[8 * j + 1] = bfhi(v.x); cf[8 * j + 2] = bflo(v.y); cf[8 * j + 3] = bfhi(v.y); cf[8 * j + 4] = bflo(v.z); cf[8 * j + 5] = bfhi(v.z); cf[8 * j + 6] = bflo(v.w); cf[8 * j + 7] = bfhi(v.w); }
; #pragma unroll
;         for (int dir = 0; dir < 2; ++dir) {
;             float z[8];
; #pragma unroll
;             for (int dd = 0; dd < 8; ++dd) z[dd] = bg[dir * 64 + 8 * dg + dd];
; #pragma unroll
;             for (int r = 0; r < 16; ++r) {
;                 const f32x4 w0 = *(const f32x4*)(wg + dir * 1024 + r * 64 + 8 * dg), w1 = *(const f32x4*)(wg + dir * 1024 + r * 64 + 8 * dg + 4);
;                 const float cv = cf[dir * 16 + r];
;                 z[0] += cv * w0[0]; z[1] += cv * w0[1]; z[2] += cv * w0[2]; z[3] += cv * w0[3]; z[4] += cv * w1[0]; z[5] += cv * w1[1]; z[6] += cv * w1[2]; z[7] += cv * w1[3];
.LBB0_572:
	s_waitcnt vmcnt(2)
	ds_read_b128 v[94:97], v35 offset:43520
	ds_read_b128 v[98:101], v35 offset:43536
	ds_read_b128 v[118:121], v35 offset:35328
	ds_read_b128 v[122:125], v35 offset:35344
	ds_read_b128 v[126:129], v35 offset:35584
	ds_read_b128 v[130:133], v35 offset:35600
	ds_read_b128 v[134:137], v35 offset:35840
	ds_read_b128 v[138:141], v35 offset:35856
	ds_read_b128 v[142:145], v35 offset:36096
	ds_read_b128 v[146:149], v35 offset:36112
	v_lshlrev_b32_e32 v102, 16, v22
	v_and_b32_e32 v103, 0xffff0000, v22
	v_lshlrev_b32_e32 v104, 16, v23
	v_and_b32_e32 v105, 0xffff0000, v23
	v_lshlrev_b32_e32 v106, 16, v24
	v_and_b32_e32 v107, 0xffff0000, v24
	v_lshlrev_b32_e32 v108, 16, v25
	v_and_b32_e32 v109, 0xffff0000, v25
	v_lshlrev_b32_e32 v110, 16, v18
	v_and_b32_e32 v111, 0xffff0000, v18
	v_lshlrev_b32_e32 v112, 16, v19
	v_and_b32_e32 v113, 0xffff0000, v19
	v_lshlrev_b32_e32 v114, 16, v20
	v_and_b32_e32 v115, 0xffff0000, v20
	v_lshlrev_b32_e32 v116, 16, v21
	v_and_b32_e32 v117, 0xffff0000, v21
	s_waitcnt lgkmcnt(6)
	v_fmac_f32_e32 v94, v118, v102
	v_fmac_f32_e32 v95, v119, v102
	v_fmac_f32_e32 v96, v120, v102
	v_fmac_f32_e32 v97, v121, v102
	v_fmac_f32_e32 v98, v122, v102
	v_fmac_f32_e32 v99, v123, v102
	v_fmac_f32_e32 v100, v124, v102
	v_fmac_f32_e32 v101, v125, v102
	ds_read_b128 v[118:121], v35 offset:36352
	ds_read_b128 v[122:125], v35 offset:36368
	s_waitcnt lgkmcnt(6)
	v_fmac_f32_e32 v94, v126, v103
	v_fmac_f32_e32 v95, v127, v103
	v_fmac_f32_e32 v96, v128, v103
	v_fmac_f32_e32 v97, v129, v103
	v_fmac_f32_e32 v98, v130, v103
	v_fmac_f32_e32 v99, v131, v103
	v_fmac_f32_e32 v100, v132, v103
	v_fmac_f32_e32 v101, v133, v103
	ds_read_b128 v[126:129], v35 offset:36608
	ds_read_b128 v[130:133], v35 offset:36624
	s_waitcnt lgkmcnt(6)
	v_fmac_f32_e32 v94, v134, v104
	v_fmac_f32_e32 v95, v135, v104
	v_fmac_f32_e32 v96, v136, v104
	v_fmac_f32_e32 v97, v137, v104
	v_fmac_f32_e32 v98, v138, v104
	v_fmac_f32_e32 v99, v139, v104
	v_fmac_f32_e32 v100, v140, v104
	v_fmac_f32_e32 v101, v141, v104
	ds_read_b128 v[134:137], v35 offset:36864
	ds_read_b128 v[138:141], v35 offset:36880
	s_waitcnt lgkmcnt(6)
	v_fmac_f32_e32 v94, v142, v105
	v_fmac_f32_e32 v95, v143, v105
	v_fmac_f32_e32 v96, v144, v105
	v_fmac_f32_e32 v97, v145, v105
	v_fmac_f32_e32 v98, v146, v105
	v_fmac_f32_e32 v99, v147, v105
	v_fmac_f32_e32 v100, v148, v105
	v_fmac_f32_e32 v101, v149, v105
	ds_read_b128 v[142:145], v35 offset:37120
	ds_read_b128 v[146:149], v35 offset:37136
	s_waitcnt lgkmcnt(6)
	v_fmac_f32_e32 v94, v118, v106
	v_fmac_f32_e32 v95, v119, v106
	v_fmac_f32_e32 v96, v120, v106
	v_fmac_f32_e32 v97, v121, v106
	v_fmac_f32_e32 v98, v122, v106
	v_fmac_f32_e32 v99, v123, v106
	v_fmac_f32_e32 v100, v124, v106
	v_fmac_f32_e32 v101, v125, v106
	ds_read_b128 v[118:121], v35 offset:37376
	ds_read_b128 v[122:125], v35 offset:37392
	s_waitcnt lgkmcnt(6)
	v_fmac_f32_e32 v94, v126, v107
	v_fmac_f32_e32 v95, v127, v107
	v_fmac_f32_e32 v96, v128, v107
	v_fmac_f32_e32 v97, v129, v107
	v_fmac_f32_e32 v98, v130, v107
	v_fmac_f32_e32 v99, v131, v107
	v_fmac_f32_e32 v100, v132, v107
	v_fmac_f32_e32 v101, v133, v107
	ds_read_b128 v[126:129], v35 offset:37632
	ds_read_b128 v[130:133], v35 offset:37648
	s_waitcnt lgkmcnt(6)
	v_fmac_f32_e32 v94, v134, v108
	v_fmac_f32_e32 v95, v135, v108
	v_fmac_f32_e32 v96, v136, v108
	v_fmac_f32_e32 v97, v137, v108
	v_fmac_f32_e32 v98, v138, v108
	v_fmac_f32_e32 v99, v139, v108
	v_fmac_f32_e32 v100, v140, v108
	v_fmac_f32_e32 v101, v141, v108
	ds_read_b128 v[134:137], v35 offset:37888
	ds_read_b128 v[138:141], v35 offset:37904
	s_waitcnt lgkmcnt(6)
	v_fmac_f32_e32 v94, v142, v109
	v_fmac_f32_e32 v95, v143, v109
	v_fmac_f32_e32 v96, v144, v109
	v_fmac_f32_e32 v97, v145, v109
	v_fmac_f32_e32 v98, v146, v109
	v_fmac_f32_e32 v99, v147, v109
	v_fmac_f32_e32 v100, v148, v109
	v_fmac_f32_e32 v101, v149, v109
	ds_read_b128 v[142:145], v35 offset:38144
	ds_read_b128 v[146:149], v35 offset:38160
	s_waitcnt lgkmcnt(6)
	v_fmac_f32_e32 v94, v118, v110
	v_fmac_f32_e32 v95, v119, v110
	v_fmac_f32_e32 v96, v120, v110
	v_fmac_f32_e32 v97, v121, v110
	v_fmac_f32_e32 v98, v122, v110
	v_fmac_f32_e32 v99, v123, v110
	v_fmac_f32_e32 v100, v124, v110
	v_fmac_f32_e32 v101, v125, v110
	ds_read_b128 v[118:121], v35 offset:38400
	ds_read_b128 v[122:125], v35 offset:38416
	s_waitcnt lgkmcnt(6)
	v_fmac_f32_e32 v94, v126, v111
	v_fmac_f32_e32 v95, v127, v111
	v_fmac_f32_e32 v96, v128, v111
	v_fmac_f32_e32 v97, v129, v111
	v_fmac_f32_e32 v98, v130, v111
	v_fmac_f32_e32 v99, v131, v111
	v_fmac_f32_e32 v100, v132, v111
	v_fmac_f32_e32 v101, v133, v111
	ds_read_b128 v[126:129], v35 offset:38656
	ds_read_b128 v[130:133], v35 offset:38672
	s_waitcnt lgkmcnt(6)
	v_fmac_f32_e32 v94, v134, v112
	v_fmac_f32_e32 v95, v135, v112
	v_fmac_f32_e32 v96, v136, v112
	v_fmac_f32_e32 v97, v137, v112
	v_fmac_f32_e32 v98, v138, v112
	v_fmac_f32_e32 v99, v139, v112
	v_fmac_f32_e32 v100, v140, v112
	v_fmac_f32_e32 v101, v141, v112
	ds_read_b128 v[134:137], v35 offset:38912
	ds_read_b128 v[138:141], v35 offset:38928
	s_waitcnt lgkmcnt(6)
	v_fmac_f32_e32 v94, v142, v113
	v_fmac_f32_e32 v95, v143, v113
	v_fmac_f32_e32 v96, v144, v113
	v_fmac_f32_e32 v97, v145, v113
	v_fmac_f32_e32 v98, v146, v113
	v_fmac_f32_e32 v99, v147, v113
	v_fmac_f32_e32 v100, v148, v113
	v_fmac_f32_e32 v101, v149, v113
	ds_read_b128 v[142:145], v35 offset:39168
	ds_read_b128 v[146:149], v35 offset:39184
	s_waitcnt lgkmcnt(6)
	v_fmac_f32_e32 v94, v118, v114
	v_fmac_f32_e32 v95, v119, v114
	v_fmac_f32_e32 v96, v120, v114
	v_fmac_f32_e32 v97, v121, v114
	v_fmac_f32_e32 v98, v122, v114
	v_fmac_f32_e32 v99, v123, v114
	v_fmac_f32_e32 v100, v124, v114
	v_fmac_f32_e32 v101, v125, v114
	s_waitcnt lgkmcnt(4)
; DI float log_sigmoid_f(float z) { return fminf(z, 0.f) - __logf(1.0f + __expf(-fabsf(z))); }
; DI void gla_prep_item(const Args& A, int l, unsigned char* ldsb, int item, int tid, bool stage) {
;     ...
;         for (int dir = 0; dir < 2; ++dir) {
;             float z[8];
; #pragma unroll
;             for (int dd = 0; dd < 8; ++dd) z[dd] = bg[dir * 64 + 8 * dg + dd];
; #pragma unroll
;             for (int r = 0; r < 16; ++r) {
;                 const f32x4 w0 = *(const f32x4*)(wg + dir * 1024 + r * 64 + 8 * dg), w1 = *(const f32x4*)(wg + dir * 1024 + r * 64 + 8 * dg + 4);
;                 const float cv = cf[dir * 16 + r];
;                 z[0] += cv * w0[0]; z[1] += cv * w0[1]; z[2] += cv * w0[2]; z[3] += cv * w0[3]; z[4] += cv * w1[0]; z[5] += cv * w1[1]; z[6] += cv * w1[2]; z[7] += cv * w1[3];
;             }
; #pragma unroll
;             for (int dd = 0; dd < 8; ++dd) gl[(dir * 64 + t) * 65 + 8 * dg + dd] = log_sigmoid_f(z[dd]) * (1.0f / 16.0f);
	v_fmac_f32_e32 v94, v126, v115
	v_fmac_f32_e32 v95, v127, v115
	v_fmac_f32_e32 v96, v128, v115
	v_fmac_f32_e32 v97, v129, v115
	v_fmac_f32_e32 v98, v130, v115
	v_fmac_f32_e32 v99, v131, v115
	v_fmac_f32_e32 v100, v132, v115
	v_fmac_f32_e32 v101, v133, v115
	s_waitcnt lgkmcnt(2)
	v_fmac_f32_e32 v94, v134, v116
	v_fmac_f32_e32 v95, v135, v116
	v_fmac_f32_e32 v96, v136, v116
	v_fmac_f32_e32 v97, v137, v116
	v_fmac_f32_e32 v98, v138, v116
	v_fmac_f32_e32 v99, v139, v116
	v_fmac_f32_e32 v100, v140, v116
	v_fmac_f32_e32 v101, v141, v116
	s_waitcnt lgkmcnt(0)
	v_fmac_f32_e32 v94, v142, v117
	v_fmac_f32_e32 v95, v143, v117
	v_fmac_f32_e32 v96, v144, v117
	v_fmac_f32_e32 v97, v145, v117
	v_fmac_f32_e32 v98, v146, v117
	v_fmac_f32_e32 v99, v147, v117
	v_fmac_f32_e32 v100, v148, v117
	v_fmac_f32_e32 v101, v149, v117
	v_mul_f32_e64 v118, |v94|, s11
	v_mul_f32_e64 v119, |v95|, s11
	v_mul_f32_e64 v120, |v96|, s11
	v_mul_f32_e64 v121, |v97|, s11
	v_mul_f32_e64 v122, |v98|, s11
	v_mul_f32_e64 v123, |v99|, s11
	v_mul_f32_e64 v124, |v100|, s11
	v_mul_f32_e64 v125, |v101|, s11
	v_exp_f32_e32 v118, v118
	v_exp_f32_e32 v119, v119
	v_exp_f32_e32 v120, v120
	v_exp_f32_e32 v121, v121
	v_exp_f32_e32 v122, v122
	v_exp_f32_e32 v123, v123
	v_exp_f32_e32 v124, v124
	v_exp_f32_e32 v125, v125
	v_min_f32_e32 v142, 0, v94
	v_min_f32_e32 v143, 0, v95
	v_min_f32_e32 v144, 0, v96
	v_min_f32_e32 v145, 0, v97
	v_min_f32_e32 v146, 0, v98
	v_min_f32_e32 v147, 0, v99
	v_min_f32_e32 v148, 0, v100
	v_min_f32_e32 v149, 0, v101
	v_add_f32_e32 v118, 1.0, v118
	v_add_f32_e32 v119, 1.0, v119
	v_add_f32_e32 v120, 1.0, v120
	v_add_f32_e32 v121, 1.0, v121
	v_add_f32_e32 v122, 1.0, v122
	v_add_f32_e32 v123, 1.0, v123
	v_add_f32_e32 v124, 1.0, v124
	v_add_f32_e32 v125, 1.0, v125
	v_log_f32_e32 v126, v118
	v_log_f32_e32 v127, v119
	v_log_f32_e32 v128, v120
	v_log_f32_e32 v129, v121
	v_log_f32_e32 v130, v122
	v_log_f32_e32 v131, v123
	v_log_f32_e32 v132, v124
	v_log_f32_e32 v133, v125
	s_nop 0
	v_mul_f32_e32 v134, 0x3f317217, v126
	v_mul_f32_e32 v135, 0x3f317217, v127
	v_mul_f32_e32 v136, 0x3f317217, v128
	v_mul_f32_e32 v137, 0x3f317217, v129
	v_mul_f32_e32 v138, 0x3f317217, v130
	v_mul_f32_e32 v139, 0x3f317217, v131
	v_mul_f32_e32 v140, 0x3f317217, v132
	v_mul_f32_e32 v141, 0x3f317217, v133
	v_fma_f32 v134, v126, s81, -v134
	v_fma_f32 v135, v127, s81, -v135
	v_fma_f32 v136, v128, s81, -v136
	v_fma_f32 v137, v129, s81, -v137
	v_fma_f32 v138, v130, s81, -v138
	v_fma_f32 v139, v131, s81, -v139
	v_fma_f32 v140, v132, s81, -v140
	v_fma_f32 v141, v133, s81, -v141
	v_fmac_f32_e32 v134, 0x3377d1cf, v126
	v_fmac_f32_e32 v135, 0x3377d1cf, v127
	v_fmac_f32_e32 v136, 0x3377d1cf, v128
	v_fmac_f32_e32 v137, 0x3377d1cf, v129
	v_fmac_f32_e32 v138, 0x3377d1cf, v130
	v_fmac_f32_e32 v139, 0x3377d1cf, v131
	v_fmac_f32_e32 v140, 0x3377d1cf, v132
	v_fmac_f32_e32 v141, 0x3377d1cf, v133
	v_fmac_f32_e32 v134, 0x3f317217, v126
	v_fmac_f32_e32 v135, 0x3f317217, v127
	v_fmac_f32_e32 v136, 0x3f317217, v128
	v_fmac_f32_e32 v137, 0x3f317217, v129
	v_fmac_f32_e32 v138, 0x3f317217, v130
	v_fmac_f32_e32 v139, 0x3f317217, v131
	v_fmac_f32_e32 v140, 0x3f317217, v132
	v_fmac_f32_e32 v141, 0x3f317217, v133
	v_sub_f32_e32 v142, v142, v134
	v_sub_f32_e32 v143, v143, v135
	v_sub_f32_e32 v144, v144, v136
	v_sub_f32_e32 v145, v145, v137
	v_sub_f32_e32 v146, v146, v138
	v_sub_f32_e32 v147, v147, v139
	v_sub_f32_e32 v148, v148, v140
	v_sub_f32_e32 v149, v149, v141
	v_mul_f32_e32 v142, s18, v142
	v_mul_f32_e32 v143, s18, v143
	v_mul_f32_e32 v144, s18, v144
	v_mul_f32_e32 v145, s18, v145
	v_mul_f32_e32 v146, s18, v146
	v_mul_f32_e32 v147, s18, v147
	v_mul_f32_e32 v148, s18, v148
	v_mul_f32_e32 v149, s18, v149
	ds_write2_b32 v37, v142, v143 offset0:0 offset1:1
	ds_write2_b32 v37, v144, v145 offset0:2 offset1:3
	ds_write2_b32 v37, v146, v147 offset0:4 offset1:5
	ds_write2_b32 v37, v148, v149 offset0:6 offset1:7
	ds_read_b128 v[94:97], v35 offset:43776
	ds_read_b128 v[98:101], v35 offset:43792
	ds_read_b128 v[118:121], v35 offset:39424
	ds_read_b128 v[122:125], v35 offset:39440
	ds_read_b128 v[126:129], v35 offset:39680
	ds_read_b128 v[130:133], v35 offset:39696
	ds_read_b128 v[134:137], v35 offset:39936
	ds_read_b128 v[138:141], v35 offset:39952
	ds_read_b128 v[142:145], v35 offset:40192
	ds_read_b128 v[146:149], v35 offset:40208
	v_lshlrev_b32_e32 v102, 16, v14
	v_and_b32_e32 v103, 0xffff0000, v14
	v_lshlrev_b32_e32 v104, 16, v15
	v_and_b32_e32 v105, 0xffff0000, v15
	v_lshlrev_b32_e32 v106, 16, v16
	v_and_b32_e32 v107, 0xffff0000, v16
	v_lshlrev_b32_e32 v108, 16, v17
	v_and_b32_e32 v109, 0xffff0000, v17
	v_lshlrev_b32_e32 v110, 16, v10
	v_and_b32_e32 v111, 0xffff0000, v10
	v_lshlrev_b32_e32 v112, 16, v11
	v_and_b32_e32 v113, 0xffff0000, v11
	v_lshlrev_b32_e32 v114, 16, v12
	v_and_b32_e32 v115, 0xffff0000, v12
	v_lshlrev_b32_e32 v116, 16, v13
	v_and_b32_e32 v117, 0xffff0000, v13
	s_waitcnt lgkmcnt(6)
	v_fmac_f32_e32 v94, v118, v102
	v_fmac_f32_e32 v95, v119, v102
	v_fmac_f32_e32 v96, v120, v102
	v_fmac_f32_e32 v97, v121, v102
	v_fmac_f32_e32 v98, v122, v102
	v_fmac_f32_e32 v99, v123, v102
	v_fmac_f32_e32 v100, v124, v102
	v_fmac_f32_e32 v101, v125, v102
	ds_read_b128 v[118:121], v35 offset:40448
	ds_read_b128 v[122:125], v35 offset:40464
	s_waitcnt lgkmcnt(6)
	v_fmac_f32_e32 v94, v126, v103
	v_fmac_f32_e32 v95, v127, v103
	v_fmac_f32_e32 v96, v128, v103
	v_fmac_f32_e32 v97, v129, v103
	v_fmac_f32_e32 v98, v130, v103
	v_fmac_f32_e32 v99, v131, v103
	v_fmac_f32_e32 v100, v132, v103
	v_fmac_f32_e32 v101, v133, v103
	ds_read_b128 v[126:129], v35 offset:40704
	ds_read_b128 v[130:133], v35 offset:40720
	s_waitcnt lgkmcnt(6)
; DI void gla_prep_item(const Args& A, int l, unsigned char* ldsb, int item, int tid, bool stage) {
;     ...
;         for (int dir = 0; dir < 2; ++dir) {
;             float z[8];
; #pragma unroll
;             for (int dd = 0; dd < 8; ++dd) z[dd] = bg[dir * 64 + 8 * dg + dd];
; #pragma unroll
;             for (int r = 0; r < 16; ++r) {
;                 const f32x4 w0 = *(const f32x4*)(wg + dir * 1024 + r * 64 + 8 * dg), w1 = *(const f32x4*)(wg + dir * 1024 + r * 64 + 8 * dg + 4);
;                 const float cv = cf[dir * 16 + r];
;                 z[0] += cv * w0[0]; z[1] += cv * w0[1]; z[2] += cv * w0[2]; z[3] += cv * w0[3]; z[4] += cv * w1[0]; z[5] += cv * w1[1]; z[6] += cv * w1[2]; z[7] += cv * w1[3];
;             }
	v_fmac_f32_e32 v94, v134, v104
	v_fmac_f32_e32 v95, v135, v104
	v_fmac_f32_e32 v96, v136, v104
	v_fmac_f32_e32 v97, v137, v104
	v_fmac_f32_e32 v98, v138, v104
	v_fmac_f32_e32 v99, v139, v104
	v_fmac_f32_e32 v100, v140, v104
	v_fmac_f32_e32 v101, v141, v104
	ds_read_b128 v[134:137], v35 offset:40960
	ds_read_b128 v[138:141], v35 offset:40976
	s_waitcnt lgkmcnt(6)
	v_fmac_f32_e32 v94, v142, v105
	v_fmac_f32_e32 v95, v143, v105
	v_fmac_f32_e32 v96, v144, v105
	v_fmac_f32_e32 v97, v145, v105
	v_fmac_f32_e32 v98, v146, v105
	v_fmac_f32_e32 v99, v147, v105
	v_fmac_f32_e32 v100, v148, v105
	v_fmac_f32_e32 v101, v149, v105
	ds_read_b128 v[142:145], v35 offset:41216
	ds_read_b128 v[146:149], v35 offset:41232
	s_waitcnt lgkmcnt(6)
	v_fmac_f32_e32 v94, v118, v106
	v_fmac_f32_e32 v95, v119, v106
	v_fmac_f32_e32 v96, v120, v106
	v_fmac_f32_e32 v97, v121, v106
	v_fmac_f32_e32 v98, v122, v106
	v_fmac_f32_e32 v99, v123, v106
	v_fmac_f32_e32 v100, v124, v106
	v_fmac_f32_e32 v101, v125, v106
	ds_read_b128 v[118:121], v35 offset:41472
	ds_read_b128 v[122:125], v35 offset:41488
	s_waitcnt lgkmcnt(6)
	v_fmac_f32_e32 v94, v126, v107
	v_fmac_f32_e32 v95, v127, v107
	v_fmac_f32_e32 v96, v128, v107
	v_fmac_f32_e32 v97, v129, v107
	v_fmac_f32_e32 v98, v130, v107
	v_fmac_f32_e32 v99, v131, v107
	v_fmac_f32_e32 v100, v132, v107
	v_fmac_f32_e32 v101, v133, v107
	ds_read_b128 v[126:129], v35 offset:41728
	ds_read_b128 v[130:133], v35 offset:41744
	s_waitcnt lgkmcnt(6)
	v_fmac_f32_e32 v94, v134, v108
	v_fmac_f32_e32 v95, v135, v108
	v_fmac_f32_e32 v96, v136, v108
	v_fmac_f32_e32 v97, v137, v108
	v_fmac_f32_e32 v98, v138, v108
	v_fmac_f32_e32 v99, v139, v108
	v_fmac_f32_e32 v100, v140, v108
	v_fmac_f32_e32 v101, v141, v108
	ds_read_b128 v[134:137], v35 offset:41984
	ds_read_b128 v[138:141], v35 offset:42000
	s_waitcnt lgkmcnt(6)
	v_fmac_f32_e32 v94, v142, v109
	v_fmac_f32_e32 v95, v143, v109
	v_fmac_f32_e32 v96, v144, v109
	v_fmac_f32_e32 v97, v145, v109
	v_fmac_f32_e32 v98, v146, v109
	v_fmac_f32_e32 v99, v147, v109
	v_fmac_f32_e32 v100, v148, v109
	v_fmac_f32_e32 v101, v149, v109
	ds_read_b128 v[142:145], v35 offset:42240
	ds_read_b128 v[146:149], v35 offset:42256
	s_waitcnt lgkmcnt(6)
	v_fmac_f32_e32 v94, v118, v110
	v_fmac_f32_e32 v95, v119, v110
	v_fmac_f32_e32 v96, v120, v110
	v_fmac_f32_e32 v97, v121, v110
	v_fmac_f32_e32 v98, v122, v110
	v_fmac_f32_e32 v99, v123, v110
	v_fmac_f32_e32 v100, v124, v110
	v_fmac_f32_e32 v101, v125, v110
	ds_read_b128 v[118:121], v35 offset:42496
	ds_read_b128 v[122:125], v35 offset:42512
	s_waitcnt lgkmcnt(6)
	v_fmac_f32_e32 v94, v126, v111
	v_fmac_f32_e32 v95, v127, v111
	v_fmac_f32_e32 v96, v128, v111
	v_fmac_f32_e32 v97, v129, v111
	v_fmac_f32_e32 v98, v130, v111
	v_fmac_f32_e32 v99, v131, v111
	v_fmac_f32_e32 v100, v132, v111
	v_fmac_f32_e32 v101, v133, v111
	ds_read_b128 v[126:129], v35 offset:42752
	ds_read_b128 v[130:133], v35 offset:42768
	s_waitcnt lgkmcnt(6)
	v_fmac_f32_e32 v94, v134, v112
	v_fmac_f32_e32 v95, v135, v112
	v_fmac_f32_e32 v96, v136, v112
	v_fmac_f32_e32 v97, v137, v112
	v_fmac_f32_e32 v98, v138, v112
	v_fmac_f32_e32 v99, v139, v112
	v_fmac_f32_e32 v100, v140, v112
	v_fmac_f32_e32 v101, v141, v112
	ds_read_b128 v[134:137], v35 offset:43008
	ds_read_b128 v[138:141], v35 offset:43024
	s_waitcnt lgkmcnt(6)
	v_fmac_f32_e32 v94, v142, v113
	v_fmac_f32_e32 v95, v143, v113
	v_fmac_f32_e32 v96, v144, v113
	v_fmac_f32_e32 v97, v145, v113
	v_fmac_f32_e32 v98, v146, v113
	v_fmac_f32_e32 v99, v147, v113
	v_fmac_f32_e32 v100, v148, v113
	v_fmac_f32_e32 v101, v149, v113
	ds_read_b128 v[142:145], v35 offset:43264
	ds_read_b128 v[146:149], v35 offset:43280
	s_waitcnt lgkmcnt(6)
	v_fmac_f32_e32 v94, v118, v114
	v_fmac_f32_e32 v95, v119, v114
	v_fmac_f32_e32 v96, v120, v114
	v_fmac_f32_e32 v97, v121, v114
	v_fmac_f32_e32 v98, v122, v114
	v_fmac_f32_e32 v99, v123, v114
	v_fmac_f32_e32 v100, v124, v114
	v_fmac_f32_e32 v101, v125, v114
	s_waitcnt lgkmcnt(4)
	v_fmac_f32_e32 v94, v126, v115
	v_fmac_f32_e32 v95, v127, v115
	v_fmac_f32_e32 v96, v128, v115
	v_fmac_f32_e32 v97, v129, v115
	v_fmac_f32_e32 v98, v130, v115
	v_fmac_f32_e32 v99, v131, v115
	v_fmac_f32_e32 v100, v132, v115
	v_fmac_f32_e32 v101, v133, v115
	s_waitcnt lgkmcnt(2)
	v_fmac_f32_e32 v94, v134, v116
	v_fmac_f32_e32 v95, v135, v116
	v_fmac_f32_e32 v96, v136, v116
	v_fmac_f32_e32 v97, v137, v116
	v_fmac_f32_e32 v98, v138, v116
	v_fmac_f32_e32 v99, v139, v116
	v_fmac_f32_e32 v100, v140, v116
	v_fmac_f32_e32 v101, v141, v116
	s_waitcnt lgkmcnt(0)
; DI float log_sigmoid_f(float z) { return fminf(z, 0.f) - __logf(1.0f + __expf(-fabsf(z))); }
; DI void gla_prep_item(const Args& A, int l, unsigned char* ldsb, int item, int tid, bool stage) {
;     ...
;             }
; #pragma unroll
;             for (int dd = 0; dd < 8; ++dd) gl[(dir * 64 + t) * 65 + 8 * dg + dd] = log_sigmoid_f(z[dd]) * (1.0f / 16.0f);
;     ...
;     __syncthreads();
;     {
;         const int dir = tid >> 8, seg = (tid >> 6) & 3, d = tid & 63;
;         float* gp = gl + (dir * 64 + 16 * seg) * 65 + d; float v[16];
; #pragma unroll
;         for (int tt = 0; tt < 16; ++tt) v[tt] = gp[tt * 65];
;         if (dir == 0) {
; #pragma unroll
;             for (int tt = 1; tt < 16; ++tt) v[tt] += v[tt - 1];
;         } else {
; #pragma unroll
	v_fmac_f32_e32 v94, v142, v117
	v_fmac_f32_e32 v95, v143, v117
	v_fmac_f32_e32 v96, v144, v117
	v_fmac_f32_e32 v97, v145, v117
	v_fmac_f32_e32 v98, v146, v117
	v_fmac_f32_e32 v99, v147, v117
	v_fmac_f32_e32 v100, v148, v117
	v_fmac_f32_e32 v101, v149, v117
	v_mul_f32_e64 v118, |v94|, s11
	v_mul_f32_e64 v119, |v95|, s11
	v_mul_f32_e64 v120, |v96|, s11
	v_mul_f32_e64 v121, |v97|, s11
	v_mul_f32_e64 v122, |v98|, s11
	v_mul_f32_e64 v123, |v99|, s11
	v_mul_f32_e64 v124, |v100|, s11
	v_mul_f32_e64 v125, |v101|, s11
	v_exp_f32_e32 v118, v118
	v_exp_f32_e32 v119, v119
	v_exp_f32_e32 v120, v120
	v_exp_f32_e32 v121, v121
	v_exp_f32_e32 v122, v122
	v_exp_f32_e32 v123, v123
	v_exp_f32_e32 v124, v124
	v_exp_f32_e32 v125, v125
	v_min_f32_e32 v142, 0, v94
	v_min_f32_e32 v143, 0, v95
	v_min_f32_e32 v144, 0, v96
	v_min_f32_e32 v145, 0, v97
	v_min_f32_e32 v146, 0, v98
	v_min_f32_e32 v147, 0, v99
	v_min_f32_e32 v148, 0, v100
	v_min_f32_e32 v149, 0, v101
	v_add_f32_e32 v118, 1.0, v118
	v_add_f32_e32 v119, 1.0, v119
	v_add_f32_e32 v120, 1.0, v120
	v_add_f32_e32 v121, 1.0, v121
	v_add_f32_e32 v122, 1.0, v122
	v_add_f32_e32 v123, 1.0, v123
	v_add_f32_e32 v124, 1.0, v124
	v_add_f32_e32 v125, 1.0, v125
	v_log_f32_e32 v126, v118
	v_log_f32_e32 v127, v119
	v_log_f32_e32 v128, v120
	v_log_f32_e32 v129, v121
	v_log_f32_e32 v130, v122
	v_log_f32_e32 v131, v123
	v_log_f32_e32 v132, v124
	v_log_f32_e32 v133, v125
	s_nop 0
	v_mul_f32_e32 v134, 0x3f317217, v126
	v_mul_f32_e32 v135, 0x3f317217, v127
	v_mul_f32_e32 v136, 0x3f317217, v128
	v_mul_f32_e32 v137, 0x3f317217, v129
	v_mul_f32_e32 v138, 0x3f317217, v130
	v_mul_f32_e32 v139, 0x3f317217, v131
	v_mul_f32_e32 v140, 0x3f317217, v132
	v_mul_f32_e32 v141, 0x3f317217, v133
	v_fma_f32 v134, v126, s81, -v134
	v_fma_f32 v135, v127, s81, -v135
	v_fma_f32 v136, v128, s81, -v136
	v_fma_f32 v137, v129, s81, -v137
	v_fma_f32 v138, v130, s81, -v138
	v_fma_f32 v139, v131, s81, -v139
	v_fma_f32 v140, v132, s81, -v140
	v_fma_f32 v141, v133, s81, -v141
	v_fmac_f32_e32 v134, 0x3377d1cf, v126
	v_fmac_f32_e32 v135, 0x3377d1cf, v127
	v_fmac_f32_e32 v136, 0x3377d1cf, v128
	v_fmac_f32_e32 v137, 0x3377d1cf, v129
	v_fmac_f32_e32 v138, 0x3377d1cf, v130
	v_fmac_f32_e32 v139, 0x3377d1cf, v131
	v_fmac_f32_e32 v140, 0x3377d1cf, v132
	v_fmac_f32_e32 v141, 0x3377d1cf, v133
	v_fmac_f32_e32 v134, 0x3f317217, v126
	v_fmac_f32_e32 v135, 0x3f317217, v127
	v_fmac_f32_e32 v136, 0x3f317217, v128
	v_fmac_f32_e32 v137, 0x3f317217, v129
	v_fmac_f32_e32 v138, 0x3f317217, v130
	v_fmac_f32_e32 v139, 0x3f317217, v131
	v_fmac_f32_e32 v140, 0x3f317217, v132
	v_fmac_f32_e32 v141, 0x3f317217, v133
	v_sub_f32_e32 v142, v142, v134
	v_sub_f32_e32 v143, v143, v135
	v_sub_f32_e32 v144, v144, v136
	v_sub_f32_e32 v145, v145, v137
	v_sub_f32_e32 v146, v146, v138
	v_sub_f32_e32 v147, v147, v139
	v_sub_f32_e32 v148, v148, v140
	v_sub_f32_e32 v149, v149, v141
	v_mul_f32_e32 v142, s18, v142
	v_mul_f32_e32 v143, s18, v143
	v_mul_f32_e32 v144, s18, v144
	v_mul_f32_e32 v145, s18, v145
	v_mul_f32_e32 v146, s18, v146
	v_mul_f32_e32 v147, s18, v147
	v_mul_f32_e32 v148, s18, v148
	v_mul_f32_e32 v149, s18, v149
	v_add_u32_e32 v47, 0x4100, v37
	v_add_u32_e32 v45, 0x4108, v37
	v_add_u32_e32 v43, 0x4110, v37
	v_add_u32_e32 v0, 0x4118, v37
	v_add_u32_e32 v52, 0x400, v32
	v_add_u32_e32 v51, 0x800, v32
	v_add_u32_e32 v50, 0xc00, v32
	ds_write2_b32 v47, v142, v143 offset1:1
	ds_write2_b32 v45, v144, v145 offset1:1
	ds_write2_b32 v43, v146, v147 offset1:1
	ds_write2_b32 v0, v148, v149 offset1:1
	s_waitcnt lgkmcnt(0)
	s_barrier
	ds_read2_b32 v[12:13], v32 offset1:65
	ds_read2_b32 v[14:15], v32 offset0:130 offset1:195
	ds_read2_b32 v[16:17], v52 offset0:4 offset1:69
	ds_read2_b32 v[18:19], v52 offset0:134 offset1:199
	ds_read2_b32 v[20:21], v51 offset0:8 offset1:73
	ds_read2_b32 v[22:23], v51 offset0:138 offset1:203
	ds_read2_b32 v[24:25], v50 offset0:12 offset1:77
	ds_read2_b32 v[10:11], v50 offset0:142 offset1:207
	s_and_saveexec_b64 s[2:3], s[42:43]
	s_xor_b64 s[2:3], exec, s[2:3]
	s_cbranch_execz .LBB0_574
	s_waitcnt lgkmcnt(0)
	v_add_f32_e32 v53, v10, v11
	v_add_f32_e32 v54, v25, v53
	v_add_f32_e32 v55, v24, v54
	v_add_f32_e32 v56, v23, v55
	v_add_f32_e32 v57, v22, v56
	v_add_f32_e32 v58, v21, v57
	v_add_f32_e32 v59, v20, v58
	v_add_f32_e32 v60, v19, v59
	v_add_f32_e32 v61, v18, v60
	v_add_f32_e32 v62, v17, v61
	v_add_f32_e32 v63, v16, v62
	v_add_f32_e32 v80, v15, v63
	v_add_f32_e32 v81, v14, v80
	v_add_f32_e32 v82, v13, v81
	v_add_f32_e32 v84, v12, v82
